# combo2 + mlB: next-but-one batch of U rows prefetched (dummy loads) after each batch wait
# speedup vs baseline: 1.0036x; 1.0036x over previous
.LBB0_1447:
	s_or_b64 exec, exec, s[4:5]
	s_waitcnt vmcnt(0) lgkmcnt(0)
	s_mov_b32 s100, 0x3b700000
	s_mov_b32 s101, 0
	v_lshl_add_u64 v[62:63], s[6:7], 0, v[6:7]
	v_lshl_add_u64 v[62:63], v[62:63], 0, s[100:101]
	global_load_dword v60, v[62:63], off
	s_mov_b32 s100, 0x10000
	v_lshl_add_u64 v[62:63], v[62:63], 0, s[100:101]
	global_load_dword v60, v[62:63], off
	v_lshl_add_u64 v[62:63], v[62:63], 0, s[100:101]
	global_load_dword v60, v[62:63], off
	v_lshl_add_u64 v[62:63], v[62:63], 0, s[100:101]
	global_load_dword v60, v[62:63], off
	v_lshl_add_u64 v[62:63], v[62:63], 0, s[100:101]
	global_load_dword v60, v[62:63], off
	v_lshl_add_u64 v[62:63], v[62:63], 0, s[100:101]
	global_load_dword v60, v[62:63], off
	v_lshl_add_u64 v[62:63], v[62:63], 0, s[100:101]
	global_load_dword v60, v[62:63], off
	v_lshl_add_u64 v[62:63], v[62:63], 0, s[100:101]
	global_load_dword v60, v[62:63], off
	v_add_f32_e32 v30, v30, v47
	v_max_f32_e32 v47, v50, v50
	v_max_f32_e32 v47, v30, v47
	v_sub_f32_e32 v50, v50, v47
	v_sub_f32_e32 v30, v30, v47
	v_mul_f32_e32 v50, 0x3fb8aa3b, v50
	v_mul_f32_e32 v30, 0x3fb8aa3b, v30
	v_exp_f32_e32 v53, v50
	v_exp_f32_e32 v52, v30
	v_add_co_u32_e32 v50, vcc, 0x43608000, v20
	v_mul_f32_e32 v30, v19, v53
	v_pk_fma_f32 v[18:19], v[18:19], v[52:53], v[30:31] op_sel_hi:[1,1,0]
	v_mul_f32_e32 v30, v53, v51
	v_fmac_f32_e32 v30, v14, v52
	v_bfe_u32 v14, v18, 16, 1
	v_add3_u32 v14, v18, v14, s88
	v_addc_co_u32_e32 v51, vcc, 0, v21, vcc
	flat_store_short_d16_hi v[50:51], v14
	s_and_saveexec_b64 s[4:5], s[36:37]
	s_cbranch_execz .LBB0_1449
	v_add_co_u32_e32 v50, vcc, 0x700000, v10
	s_nop 1
	v_addc_co_u32_e32 v51, vcc, 0, v11, vcc
	flat_store_dword v[50:51], v30 offset:512
